# v20 + windowed C loop: counted LDS waits in front of the QK MFMAs instead of one full drain
# speedup vs baseline: 1.0253x; 1.0013x over previous
; #define LAS __attribute__((address_space(3)))
; DI s16x4 vtr(const LAS unsigned char* p) { return __builtin_bit_cast(s16x4, __builtin_amdgcn_ds_read_tr16_b64_v4i16((LAS s16x4*)p)); }
; template <int DQK, bool WIN>
; DI void attn_run(int wv, const bf16_t* Qrow0, int qs, const bf16_t* Kb, int ks, const bf16_t* Vb, int vs,
;                  int kt0, int kt1, int qpos0, int window, LAS unsigned char* lds, f32x16 (&o)[2], float& m_out, float& l_out) {
;     ...
;         if (WIN) need = (64 * kt + 63 >= qpos0 - window) && (64 * kt <= qpos0 + 31 + window);
;         if (need) {
;             const LAS unsigned char* base = lds + buf * BUF;
;             bf16x8 kf0[NDS], kf1[NDS];
; #pragma unroll
;             for (int ds = 0; ds < NDS; ++ds) {
;                 kf0[ds] = *(const LAS bf16x8*)(base + kfo + ds * 32);
;                 kf1[ds] = *(const LAS bf16x8*)(base + kfo + 32 * KP + ds * 32);
;             }
;             __builtin_amdgcn_s_setprio(1);
;             f32x16 p0 = __builtin_amdgcn_mfma_f32_32x32x16_bf16(kf0[0], q[0], negm, 0, 0, 0);
;             f32x16 p1 = __builtin_amdgcn_mfma_f32_32x32x16_bf16(kf1[0], q[0], negm, 0, 0, 0);
; #pragma unroll
;             for (int ds = 1; ds < NDS; ++ds) {
;                 p0 = __builtin_amdgcn_mfma_f32_32x32x16_bf16(kf0[ds], q[ds], p0, 0, 0, 0);
;                 p1 = __builtin_amdgcn_mfma_f32_32x32x16_bf16(kf1[ds], q[ds], p1, 0, 0, 0);
;             }
;             __builtin_amdgcn_s_setprio(0);
;             s16x4 vlo[4][2], vhi[4][2];
; #pragma unroll
;             for (int k4 = 0; k4 < 4; ++k4)
; #pragma unroll
;                 for (int db = 0; db < 2; ++db) {
;                     vlo[k4][db] = vtr(base + vfo + (16 * k4) * VP + 64 * db);
;                     vhi[k4][db] = vtr(base + vfo + (16 * k4 + 8) * VP + 64 * db);
;                 }
.Lew_c_skip:
	s_add_i32 s30, s36, 63
	s_cmp_ge_i32 s30, s75
	s_cselect_b64 s[30:31], -1, 0
	s_cmp_le_u32 s36, s14
	s_cselect_b64 s[36:37], -1, 0
	s_and_b64 s[30:31], s[30:31], s[36:37]
	s_andn2_b64 vcc, exec, s[30:31]
	s_cbranch_vccnz .LBB0_1281
	s_mul_i32 s30, s15, 0x5400
	s_add_i32 s36, s30, 0
	v_add3_u32 v52, s36, v154, v144
	ds_read_b128 v[48:51], v52
	ds_read_b128 v[112:115], v52 offset:32
	ds_read_b128 v[116:119], v52 offset:4608
	ds_read_b128 v[120:123], v52 offset:4640
	ds_read_b128 v[124:127], v52 offset:64
	ds_read_b128 v[146:149], v52 offset:96
	ds_read_b128 v[162:165], v52 offset:4672
	ds_read_b128 v[166:169], v52 offset:4704
	s_xor_b64 s[30:31], s[28:29], -1
	s_setprio 1
	s_waitcnt lgkmcnt(7)
	v_mfma_f32_32x32x16_bf16 v[64:79], v[48:51], v[80:83], v[32:47]
	s_waitcnt lgkmcnt(5)
	v_mfma_f32_32x32x16_bf16 v[48:63], v[116:119], v[80:83], v[32:47]
	s_setprio 0
	v_mfma_f32_32x32x16_bf16 v[64:79], v[112:115], v[84:87], v[64:79]
	v_add_u32_e32 v112, s36, v156
	v_add3_u32 v152, v112, v155, v157
	s_waitcnt lgkmcnt(4)
	v_mfma_f32_32x32x16_bf16 v[48:63], v[120:123], v[84:87], v[48:63]
	s_waitcnt lgkmcnt(3)
	v_mfma_f32_32x32x16_bf16 v[64:79], v[124:127], v[88:91], v[64:79]
	ds_read_b64_tr_b16 v[132:133], v152 offset:9216
	ds_read_b64_tr_b16 v[134:135], v152 offset:10752
	ds_read_b64_tr_b16 v[130:131], v152 offset:10816
	ds_read_b64_tr_b16 v[128:129], v152 offset:9280
	ds_read_b64_tr_b16 v[124:125], v152 offset:12288
	ds_read_b64_tr_b16 v[126:127], v152 offset:13824
	ds_read_b64_tr_b16 v[122:123], v152 offset:13888
	ds_read_b64_tr_b16 v[120:121], v152 offset:12352
	ds_read_b64_tr_b16 v[116:117], v152 offset:15360
	ds_read_b64_tr_b16 v[118:119], v152 offset:16896
	ds_read_b64_tr_b16 v[114:115], v152 offset:16960
	ds_read_b64_tr_b16 v[112:113], v152 offset:15424
	s_waitcnt lgkmcnt(13)
	v_mfma_f32_32x32x16_bf16 v[48:63], v[162:165], v[88:91], v[48:63]
	v_mfma_f32_32x32x16_bf16 v[64:79], v[146:149], v[92:95], v[64:79]
	s_waitcnt lgkmcnt(12)
	v_mfma_f32_32x32x16_bf16 v[48:63], v[166:169], v[92:95], v[48:63]
	s_cmp_eq_u32 m0, 1
	s_cbranch_scc0 .Lwc_slow
	s_nop 8
	v_mov_b32_e32 v142, v64
	v_mov_b32_e32 v64, v48
	v_mov_b32_e32 v143, v65
	v_mov_b32_e32 v65, v49
	v_mov_b32_e32 v146, v66
	v_mov_b32_e32 v66, v50
	v_mov_b32_e32 v147, v67
	v_mov_b32_e32 v67, v51
	v_mov_b32_e32 v148, v68
	v_mov_b32_e32 v68, v52
	v_mov_b32_e32 v149, v69
	v_mov_b32_e32 v69, v53
	v_mov_b32_e32 v150, v70
	v_mov_b32_e32 v70, v54
	v_mov_b32_e32 v151, v71
	v_mov_b32_e32 v71, v55
	s_branch .Lwc_join
